# SwiGLU epilogue H stores marked nt
# speedup vs baseline: 1.0016x; 1.0016x over previous
.LBB0_195:
	v_pk_mul_f32 v[166:167], v[120:121], s[24:25] op_sel_hi:[1,0]
	v_pk_mul_f32 v[120:121], v[124:125], v[120:121]
	v_pk_mul_f32 v[124:125], v[112:113], s[24:25] op_sel_hi:[1,0]
	v_pk_mul_f32 v[112:113], v[116:117], v[112:113]
	v_exp_f32_e32 v124, v124
	v_exp_f32_e32 v125, v125
	v_pk_mul_f32 v[126:127], v[126:127], v[122:123]
	v_pk_mul_f32 v[122:123], v[122:123], s[24:25] op_sel_hi:[1,0]
	v_exp_f32_e32 v166, v166
	v_pk_add_f32 v[124:125], v[124:125], 1.0 op_sel_hi:[1,0]
	v_exp_f32_e32 v167, v167
	v_rcp_f32_e32 v124, v124
	v_rcp_f32_e32 v125, v125
	v_exp_f32_e32 v122, v122
	v_exp_f32_e32 v123, v123
	v_pk_add_f32 v[166:167], v[166:167], 1.0 op_sel_hi:[1,0]
	v_pk_mul_f32 v[116:117], v[112:113], v[124:125]
	v_pk_mul_f32 v[112:113], v[114:115], s[24:25] op_sel_hi:[1,0]
	v_pk_add_f32 v[122:123], v[122:123], 1.0 op_sel_hi:[1,0]
	v_exp_f32_e32 v112, v112
	v_exp_f32_e32 v113, v113
	v_readlane_b32 s6, v252, 6
	v_rcp_f32_e32 v166, v166
	v_rcp_f32_e32 v167, v167
	v_pk_add_f32 v[112:113], v[112:113], 1.0 op_sel_hi:[1,0]
	v_rcp_f32_e32 v122, v122
	v_rcp_f32_e32 v112, v112
	v_rcp_f32_e32 v113, v113
	v_rcp_f32_e32 v123, v123
	v_lshl_or_b32 v162, s91, 7, v142
	v_readlane_b32 s7, v252, 7
	v_lshl_add_u32 v160, s93, 8, v140
	v_ashrrev_i32_e32 v163, 31, v162
	v_mov_b64_e32 v[138:139], s[6:7]
	v_pk_mul_f32 v[118:119], v[118:119], v[114:115]
	v_mad_i64_i32 v[164:165], s[6:7], v160, s87, v[138:139]
	v_pk_mul_f32 v[118:119], v[118:119], v[112:113]
	v_lshlrev_b64 v[112:113], 1, v[162:163]
	v_pk_mul_f32 v[120:121], v[120:121], v[166:167]
	v_pk_mul_f32 v[122:123], v[126:127], v[122:123]
	v_lshl_add_u64 v[124:125], v[164:165], 0, v[112:113]
	v_cvt_pk_bf16_f32 v114, v120, v121
	v_cvt_pk_bf16_f32 v115, v122, v123
	v_cvt_pk_bf16_f32 v116, v116, v117
	v_cvt_pk_bf16_f32 v117, v118, v119
	global_store_dwordx4 v[124:125], v[114:117], off nt
	v_pk_mul_f32 v[110:111], v[110:111], v[106:107]
	v_pk_mul_f32 v[106:107], v[106:107], s[24:25] op_sel_hi:[1,0]
	v_pk_mul_f32 v[116:117], v[104:105], s[24:25] op_sel_hi:[1,0]
	v_pk_mul_f32 v[104:105], v[108:109], v[104:105]
	v_pk_mul_f32 v[108:109], v[96:97], s[24:25] op_sel_hi:[1,0]
	v_pk_mul_f32 v[96:97], v[100:101], v[96:97]
	v_exp_f32_e32 v108, v108
	v_exp_f32_e32 v109, v109
	v_exp_f32_e32 v116, v116
	v_exp_f32_e32 v117, v117
	v_exp_f32_e32 v106, v106
	v_pk_add_f32 v[108:109], v[108:109], 1.0 op_sel_hi:[1,0]
	v_exp_f32_e32 v107, v107
	v_rcp_f32_e32 v108, v108
	v_rcp_f32_e32 v109, v109
	v_pk_add_f32 v[116:117], v[116:117], 1.0 op_sel_hi:[1,0]
	v_pk_add_f32 v[106:107], v[106:107], 1.0 op_sel_hi:[1,0]
	v_rcp_f32_e32 v116, v116
	v_pk_mul_f32 v[100:101], v[96:97], v[108:109]
	v_pk_mul_f32 v[96:97], v[98:99], s[24:25] op_sel_hi:[1,0]
	v_rcp_f32_e32 v117, v117
	v_exp_f32_e32 v96, v96
	v_exp_f32_e32 v97, v97
	v_rcp_f32_e32 v106, v106
	v_rcp_f32_e32 v107, v107
	v_or_b32_e32 v114, 16, v160
	v_pk_add_f32 v[96:97], v[96:97], 1.0 op_sel_hi:[1,0]
	v_mad_i64_i32 v[114:115], s[6:7], v114, s87, v[138:139]
	v_rcp_f32_e32 v96, v96
	v_rcp_f32_e32 v97, v97
	v_pk_mul_f32 v[102:103], v[102:103], v[98:99]
	v_pk_mul_f32 v[104:105], v[104:105], v[116:117]
	v_pk_mul_f32 v[106:107], v[110:111], v[106:107]
	v_pk_mul_f32 v[102:103], v[102:103], v[96:97]
	v_lshl_add_u64 v[108:109], v[114:115], 0, v[112:113]
	v_cvt_pk_bf16_f32 v96, v104, v105
	v_cvt_pk_bf16_f32 v97, v106, v107
	v_cvt_pk_bf16_f32 v98, v100, v101
	v_cvt_pk_bf16_f32 v99, v102, v103
	global_store_dwordx4 v[108:109], v[96:99], off nt
	v_pk_mul_f32 v[94:95], v[94:95], v[90:91]
	v_pk_mul_f32 v[90:91], v[90:91], s[24:25] op_sel_hi:[1,0]
	v_pk_mul_f32 v[98:99], v[88:89], s[24:25] op_sel_hi:[1,0]
	v_pk_mul_f32 v[88:89], v[92:93], v[88:89]
	v_pk_mul_f32 v[92:93], v[80:81], s[24:25] op_sel_hi:[1,0]
	v_pk_mul_f32 v[80:81], v[84:85], v[80:81]
	v_exp_f32_e32 v92, v92
	v_exp_f32_e32 v93, v93
	v_exp_f32_e32 v98, v98
	v_exp_f32_e32 v99, v99
	v_exp_f32_e32 v90, v90
	v_pk_add_f32 v[92:93], v[92:93], 1.0 op_sel_hi:[1,0]
	v_exp_f32_e32 v91, v91
	v_rcp_f32_e32 v92, v92
	v_rcp_f32_e32 v93, v93
	v_pk_add_f32 v[98:99], v[98:99], 1.0 op_sel_hi:[1,0]
	v_pk_add_f32 v[90:91], v[90:91], 1.0 op_sel_hi:[1,0]
	v_rcp_f32_e32 v98, v98
	v_pk_mul_f32 v[84:85], v[80:81], v[92:93]
	v_pk_mul_f32 v[80:81], v[82:83], s[24:25] op_sel_hi:[1,0]
	v_rcp_f32_e32 v99, v99
	v_exp_f32_e32 v80, v80
	v_exp_f32_e32 v81, v81
	v_rcp_f32_e32 v90, v90
	v_rcp_f32_e32 v91, v91
	v_or_b32_e32 v96, 32, v160
	v_pk_add_f32 v[80:81], v[80:81], 1.0 op_sel_hi:[1,0]
	v_mad_i64_i32 v[96:97], s[6:7], v96, s87, v[138:139]
	v_rcp_f32_e32 v80, v80
	v_rcp_f32_e32 v81, v81
	v_pk_mul_f32 v[86:87], v[86:87], v[82:83]
	v_pk_mul_f32 v[88:89], v[88:89], v[98:99]
	v_pk_mul_f32 v[90:91], v[94:95], v[90:91]
	v_pk_mul_f32 v[86:87], v[86:87], v[80:81]
	v_lshl_add_u64 v[92:93], v[96:97], 0, v[112:113]
	v_cvt_pk_bf16_f32 v80, v88, v89
	v_cvt_pk_bf16_f32 v81, v90, v91
	v_cvt_pk_bf16_f32 v82, v84, v85
	v_cvt_pk_bf16_f32 v83, v86, v87
	global_store_dwordx4 v[92:93], v[80:83], off nt
	v_pk_mul_f32 v[78:79], v[78:79], v[74:75]
	v_pk_mul_f32 v[74:75], v[74:75], s[24:25] op_sel_hi:[1,0]
	v_pk_mul_f32 v[82:83], v[72:73], s[24:25] op_sel_hi:[1,0]
	v_pk_mul_f32 v[72:73], v[76:77], v[72:73]
	v_pk_mul_f32 v[76:77], v[64:65], s[24:25] op_sel_hi:[1,0]
	v_pk_mul_f32 v[64:65], v[68:69], v[64:65]
	v_exp_f32_e32 v76, v76
	v_exp_f32_e32 v77, v77
	v_exp_f32_e32 v82, v82
	v_exp_f32_e32 v83, v83
	v_exp_f32_e32 v74, v74
	v_pk_add_f32 v[76:77], v[76:77], 1.0 op_sel_hi:[1,0]
	v_exp_f32_e32 v75, v75
	v_rcp_f32_e32 v76, v76
	v_rcp_f32_e32 v77, v77
	v_pk_add_f32 v[82:83], v[82:83], 1.0 op_sel_hi:[1,0]
	v_pk_add_f32 v[74:75], v[74:75], 1.0 op_sel_hi:[1,0]
	v_rcp_f32_e32 v82, v82
	v_pk_mul_f32 v[68:69], v[64:65], v[76:77]
	v_pk_mul_f32 v[64:65], v[66:67], s[24:25] op_sel_hi:[1,0]
	v_rcp_f32_e32 v83, v83
	v_exp_f32_e32 v64, v64
	v_exp_f32_e32 v65, v65
	v_rcp_f32_e32 v74, v74
	v_rcp_f32_e32 v75, v75
	v_or_b32_e32 v80, 48, v160
	v_pk_add_f32 v[64:65], v[64:65], 1.0 op_sel_hi:[1,0]
	v_mad_i64_i32 v[80:81], s[6:7], v80, s87, v[138:139]
	v_rcp_f32_e32 v64, v64
	v_rcp_f32_e32 v65, v65
	v_pk_mul_f32 v[70:71], v[70:71], v[66:67]
	v_pk_mul_f32 v[72:73], v[72:73], v[82:83]
	v_pk_mul_f32 v[74:75], v[78:79], v[74:75]
	v_pk_mul_f32 v[70:71], v[70:71], v[64:65]
	v_lshl_add_u64 v[76:77], v[80:81], 0, v[112:113]
	v_cvt_pk_bf16_f32 v64, v72, v73
	v_cvt_pk_bf16_f32 v65, v74, v75
	v_cvt_pk_bf16_f32 v66, v68, v69
	v_cvt_pk_bf16_f32 v67, v70, v71
	global_store_dwordx4 v[76:77], v[64:67], off nt
	v_pk_mul_f32 v[62:63], v[62:63], v[58:59]
	v_pk_mul_f32 v[58:59], v[58:59], s[24:25] op_sel_hi:[1,0]
	v_pk_mul_f32 v[66:67], v[56:57], s[24:25] op_sel_hi:[1,0]
	v_pk_mul_f32 v[56:57], v[60:61], v[56:57]
	v_pk_mul_f32 v[60:61], v[48:49], s[24:25] op_sel_hi:[1,0]
	v_pk_mul_f32 v[48:49], v[52:53], v[48:49]
	v_exp_f32_e32 v60, v60
	v_exp_f32_e32 v61, v61
	v_exp_f32_e32 v66, v66
	v_exp_f32_e32 v67, v67
	v_exp_f32_e32 v58, v58
	v_pk_add_f32 v[60:61], v[60:61], 1.0 op_sel_hi:[1,0]
	v_exp_f32_e32 v59, v59
	v_rcp_f32_e32 v60, v60
	v_rcp_f32_e32 v61, v61
	v_pk_add_f32 v[66:67], v[66:67], 1.0 op_sel_hi:[1,0]
	v_pk_add_f32 v[58:59], v[58:59], 1.0 op_sel_hi:[1,0]
	v_rcp_f32_e32 v66, v66
	v_pk_mul_f32 v[52:53], v[48:49], v[60:61]
	v_pk_mul_f32 v[48:49], v[50:51], s[24:25] op_sel_hi:[1,0]
	v_rcp_f32_e32 v67, v67
	v_exp_f32_e32 v48, v48
	v_exp_f32_e32 v49, v49
	v_rcp_f32_e32 v58, v58
	v_rcp_f32_e32 v59, v59
	v_add_u32_e32 v64, 0x80, v160
	v_pk_add_f32 v[48:49], v[48:49], 1.0 op_sel_hi:[1,0]
	v_mad_i64_i32 v[64:65], s[6:7], v64, s87, v[138:139]
	v_rcp_f32_e32 v48, v48
	v_rcp_f32_e32 v49, v49
	v_pk_mul_f32 v[54:55], v[54:55], v[50:51]
	v_pk_mul_f32 v[56:57], v[56:57], v[66:67]
	v_pk_mul_f32 v[58:59], v[62:63], v[58:59]
	v_pk_mul_f32 v[54:55], v[54:55], v[48:49]
	v_lshl_add_u64 v[60:61], v[64:65], 0, v[112:113]
	v_cvt_pk_bf16_f32 v48, v56, v57
	v_cvt_pk_bf16_f32 v49, v58, v59
	v_cvt_pk_bf16_f32 v50, v52, v53
	v_cvt_pk_bf16_f32 v51, v54, v55
	global_store_dwordx4 v[60:61], v[48:51], off nt
	v_pk_mul_f32 v[46:47], v[46:47], v[42:43]
	v_pk_mul_f32 v[42:43], v[42:43], s[24:25] op_sel_hi:[1,0]
	v_pk_mul_f32 v[50:51], v[40:41], s[24:25] op_sel_hi:[1,0]
	v_pk_mul_f32 v[40:41], v[44:45], v[40:41]
	v_pk_mul_f32 v[44:45], v[32:33], s[24:25] op_sel_hi:[1,0]
	v_pk_mul_f32 v[32:33], v[36:37], v[32:33]
	v_exp_f32_e32 v44, v44
	v_exp_f32_e32 v45, v45
	v_exp_f32_e32 v50, v50
	v_exp_f32_e32 v51, v51
	v_exp_f32_e32 v42, v42
	v_pk_add_f32 v[44:45], v[44:45], 1.0 op_sel_hi:[1,0]
	v_exp_f32_e32 v43, v43
	v_rcp_f32_e32 v44, v44
	v_rcp_f32_e32 v45, v45
	v_pk_add_f32 v[50:51], v[50:51], 1.0 op_sel_hi:[1,0]
	v_pk_add_f32 v[42:43], v[42:43], 1.0 op_sel_hi:[1,0]
	v_rcp_f32_e32 v50, v50
	v_pk_mul_f32 v[36:37], v[32:33], v[44:45]
	v_pk_mul_f32 v[32:33], v[34:35], s[24:25] op_sel_hi:[1,0]
	v_rcp_f32_e32 v51, v51
	v_exp_f32_e32 v32, v32
	v_exp_f32_e32 v33, v33
	v_rcp_f32_e32 v42, v42
	v_rcp_f32_e32 v43, v43
	v_add_u32_e32 v48, 0x90, v160
	v_pk_add_f32 v[32:33], v[32:33], 1.0 op_sel_hi:[1,0]
	v_mad_i64_i32 v[48:49], s[6:7], v48, s87, v[138:139]
	v_rcp_f32_e32 v32, v32
	v_rcp_f32_e32 v33, v33
	v_pk_mul_f32 v[38:39], v[38:39], v[34:35]
	v_pk_mul_f32 v[40:41], v[40:41], v[50:51]
	v_pk_mul_f32 v[42:43], v[46:47], v[42:43]
	v_pk_mul_f32 v[38:39], v[38:39], v[32:33]
	v_lshl_add_u64 v[44:45], v[48:49], 0, v[112:113]
	v_cvt_pk_bf16_f32 v32, v40, v41
	v_cvt_pk_bf16_f32 v33, v42, v43
	v_cvt_pk_bf16_f32 v34, v36, v37
	v_cvt_pk_bf16_f32 v35, v38, v39
	global_store_dwordx4 v[44:45], v[32:35], off nt
	v_pk_mul_f32 v[30:31], v[30:31], v[26:27]
	v_pk_mul_f32 v[26:27], v[26:27], s[24:25] op_sel_hi:[1,0]
	v_pk_mul_f32 v[34:35], v[24:25], s[24:25] op_sel_hi:[1,0]
	v_pk_mul_f32 v[24:25], v[28:29], v[24:25]
	v_pk_mul_f32 v[28:29], v[16:17], s[24:25] op_sel_hi:[1,0]
	v_pk_mul_f32 v[16:17], v[20:21], v[16:17]
	v_exp_f32_e32 v28, v28
	v_exp_f32_e32 v29, v29
	v_exp_f32_e32 v34, v34
	v_exp_f32_e32 v35, v35
	v_exp_f32_e32 v26, v26
	v_pk_add_f32 v[28:29], v[28:29], 1.0 op_sel_hi:[1,0]
	v_exp_f32_e32 v27, v27
	v_rcp_f32_e32 v28, v28
	v_rcp_f32_e32 v29, v29
	v_pk_add_f32 v[34:35], v[34:35], 1.0 op_sel_hi:[1,0]
	v_pk_add_f32 v[26:27], v[26:27], 1.0 op_sel_hi:[1,0]
	v_rcp_f32_e32 v34, v34
	v_pk_mul_f32 v[20:21], v[16:17], v[28:29]
	v_pk_mul_f32 v[16:17], v[18:19], s[24:25] op_sel_hi:[1,0]
	v_rcp_f32_e32 v35, v35
	v_exp_f32_e32 v16, v16
	v_exp_f32_e32 v17, v17
	v_rcp_f32_e32 v26, v26
	v_rcp_f32_e32 v27, v27
	v_add_u32_e32 v32, 0xa0, v160
	v_pk_add_f32 v[16:17], v[16:17], 1.0 op_sel_hi:[1,0]
	v_mad_i64_i32 v[32:33], s[6:7], v32, s87, v[138:139]
	v_rcp_f32_e32 v16, v16
	v_rcp_f32_e32 v17, v17
	v_pk_mul_f32 v[22:23], v[22:23], v[18:19]
	v_pk_mul_f32 v[24:25], v[24:25], v[34:35]
	v_pk_mul_f32 v[26:27], v[30:31], v[26:27]
	v_pk_mul_f32 v[22:23], v[22:23], v[16:17]
	v_lshl_add_u64 v[28:29], v[32:33], 0, v[112:113]
	v_cvt_pk_bf16_f32 v16, v24, v25
	v_cvt_pk_bf16_f32 v17, v26, v27
	v_cvt_pk_bf16_f32 v18, v20, v21
	v_cvt_pk_bf16_f32 v19, v22, v23
	global_store_dwordx4 v[28:29], v[16:19], off nt
	v_pk_mul_f32 v[14:15], v[14:15], v[10:11]
	v_pk_mul_f32 v[10:11], v[10:11], s[24:25] op_sel_hi:[1,0]
	v_pk_mul_f32 v[18:19], v[8:9], s[24:25] op_sel_hi:[1,0]
	v_pk_mul_f32 v[8:9], v[12:13], v[8:9]
	v_pk_mul_f32 v[12:13], v[0:1], s[24:25] op_sel_hi:[1,0]
	v_pk_mul_f32 v[0:1], v[4:5], v[0:1]
	v_exp_f32_e32 v12, v12
	v_exp_f32_e32 v13, v13
	v_exp_f32_e32 v18, v18
	v_exp_f32_e32 v19, v19
	v_exp_f32_e32 v10, v10
	v_pk_add_f32 v[12:13], v[12:13], 1.0 op_sel_hi:[1,0]
	v_exp_f32_e32 v11, v11
	v_rcp_f32_e32 v12, v12
	v_rcp_f32_e32 v13, v13
	v_pk_add_f32 v[18:19], v[18:19], 1.0 op_sel_hi:[1,0]
	v_pk_add_f32 v[10:11], v[10:11], 1.0 op_sel_hi:[1,0]
	v_rcp_f32_e32 v18, v18
	v_pk_mul_f32 v[4:5], v[0:1], v[12:13]
	v_pk_mul_f32 v[0:1], v[2:3], s[24:25] op_sel_hi:[1,0]
	v_rcp_f32_e32 v19, v19
	v_exp_f32_e32 v0, v0
	v_exp_f32_e32 v1, v1
	v_rcp_f32_e32 v10, v10
	v_rcp_f32_e32 v11, v11
	v_add_u32_e32 v16, 0xb0, v160
	v_pk_add_f32 v[0:1], v[0:1], 1.0 op_sel_hi:[1,0]
	v_mad_i64_i32 v[16:17], s[6:7], v16, s87, v[138:139]
	v_rcp_f32_e32 v0, v0
	v_rcp_f32_e32 v1, v1
	v_pk_mul_f32 v[6:7], v[6:7], v[2:3]
	v_lshl_add_u64 v[12:13], v[16:17], 0, v[112:113]
	s_and_b64 vcc, exec, s[40:41]
	s_mov_b32 s91, s71
	s_mov_b32 s93, s89
	s_mov_b64 s[6:7], s[44:45]
	s_mov_b64 s[8:9], s[42:43]
	v_pk_mul_f32 v[8:9], v[8:9], v[18:19]
	v_pk_mul_f32 v[10:11], v[14:15], v[10:11]
	v_pk_mul_f32 v[6:7], v[6:7], v[0:1]
	v_cvt_pk_bf16_f32 v0, v8, v9
	v_cvt_pk_bf16_f32 v1, v10, v11
	v_cvt_pk_bf16_f32 v2, v4, v5
	s_nop 0
	v_cvt_pk_bf16_f32 v3, v6, v7
	global_store_dwordx4 v[12:13], v[0:3], off nt
	s_cbranch_vccnz .LBB0_205

.LBB0_1050:
	v_pk_mul_f32 v[166:167], v[120:121], s[24:25] op_sel_hi:[1,0]
	v_pk_mul_f32 v[120:121], v[124:125], v[120:121]
	v_pk_mul_f32 v[124:125], v[112:113], s[24:25] op_sel_hi:[1,0]
	v_pk_mul_f32 v[112:113], v[116:117], v[112:113]
	v_exp_f32_e32 v124, v124
	v_exp_f32_e32 v125, v125
	v_pk_mul_f32 v[126:127], v[126:127], v[122:123]
	v_pk_mul_f32 v[122:123], v[122:123], s[24:25] op_sel_hi:[1,0]
	v_exp_f32_e32 v166, v166
	v_pk_add_f32 v[124:125], v[124:125], 1.0 op_sel_hi:[1,0]
	v_exp_f32_e32 v167, v167
	v_rcp_f32_e32 v124, v124
	v_rcp_f32_e32 v125, v125
	v_exp_f32_e32 v122, v122
	v_exp_f32_e32 v123, v123
	v_pk_add_f32 v[166:167], v[166:167], 1.0 op_sel_hi:[1,0]
	v_pk_mul_f32 v[116:117], v[112:113], v[124:125]
	v_pk_mul_f32 v[112:113], v[114:115], s[24:25] op_sel_hi:[1,0]
	v_pk_add_f32 v[122:123], v[122:123], 1.0 op_sel_hi:[1,0]
	v_exp_f32_e32 v112, v112
	v_exp_f32_e32 v113, v113
	v_readlane_b32 s6, v252, 6
	v_rcp_f32_e32 v166, v166
	v_rcp_f32_e32 v167, v167
	v_pk_add_f32 v[112:113], v[112:113], 1.0 op_sel_hi:[1,0]
	v_rcp_f32_e32 v122, v122
	v_rcp_f32_e32 v112, v112
	v_rcp_f32_e32 v113, v113
	v_rcp_f32_e32 v123, v123
	v_lshl_or_b32 v162, s69, 7, v142
	v_readlane_b32 s7, v252, 7
	v_lshl_add_u32 v160, s70, 8, v140
	v_ashrrev_i32_e32 v163, 31, v162
	v_mov_b64_e32 v[138:139], s[6:7]
	v_pk_mul_f32 v[118:119], v[118:119], v[114:115]
	v_mad_i64_i32 v[164:165], s[6:7], v160, s87, v[138:139]
	v_pk_mul_f32 v[118:119], v[118:119], v[112:113]
	v_lshlrev_b64 v[112:113], 1, v[162:163]
	v_pk_mul_f32 v[120:121], v[120:121], v[166:167]
	v_pk_mul_f32 v[122:123], v[126:127], v[122:123]
	v_lshl_add_u64 v[124:125], v[164:165], 0, v[112:113]
	v_cvt_pk_bf16_f32 v114, v120, v121
	v_cvt_pk_bf16_f32 v115, v122, v123
	v_cvt_pk_bf16_f32 v116, v116, v117
	v_cvt_pk_bf16_f32 v117, v118, v119
	global_store_dwordx4 v[124:125], v[114:117], off nt
	v_pk_mul_f32 v[110:111], v[110:111], v[106:107]
	v_pk_mul_f32 v[106:107], v[106:107], s[24:25] op_sel_hi:[1,0]
	v_pk_mul_f32 v[116:117], v[104:105], s[24:25] op_sel_hi:[1,0]
	v_pk_mul_f32 v[104:105], v[108:109], v[104:105]
	v_pk_mul_f32 v[108:109], v[96:97], s[24:25] op_sel_hi:[1,0]
	v_pk_mul_f32 v[96:97], v[100:101], v[96:97]
	v_exp_f32_e32 v108, v108
	v_exp_f32_e32 v109, v109
	v_exp_f32_e32 v116, v116
	v_exp_f32_e32 v117, v117
	v_exp_f32_e32 v106, v106
	v_pk_add_f32 v[108:109], v[108:109], 1.0 op_sel_hi:[1,0]
	v_exp_f32_e32 v107, v107
	v_rcp_f32_e32 v108, v108
	v_rcp_f32_e32 v109, v109
	v_pk_add_f32 v[116:117], v[116:117], 1.0 op_sel_hi:[1,0]
	v_pk_add_f32 v[106:107], v[106:107], 1.0 op_sel_hi:[1,0]
	v_rcp_f32_e32 v116, v116
	v_pk_mul_f32 v[100:101], v[96:97], v[108:109]
	v_pk_mul_f32 v[96:97], v[98:99], s[24:25] op_sel_hi:[1,0]
	v_rcp_f32_e32 v117, v117
	v_exp_f32_e32 v96, v96
	v_exp_f32_e32 v97, v97
	v_rcp_f32_e32 v106, v106
	v_rcp_f32_e32 v107, v107
	v_or_b32_e32 v114, 16, v160
	v_pk_add_f32 v[96:97], v[96:97], 1.0 op_sel_hi:[1,0]
	v_mad_i64_i32 v[114:115], s[6:7], v114, s87, v[138:139]
	v_rcp_f32_e32 v96, v96
	v_rcp_f32_e32 v97, v97
	v_pk_mul_f32 v[102:103], v[102:103], v[98:99]
	v_pk_mul_f32 v[104:105], v[104:105], v[116:117]
	v_pk_mul_f32 v[106:107], v[110:111], v[106:107]
	v_pk_mul_f32 v[102:103], v[102:103], v[96:97]
	v_lshl_add_u64 v[108:109], v[114:115], 0, v[112:113]
	v_cvt_pk_bf16_f32 v96, v104, v105
	v_cvt_pk_bf16_f32 v97, v106, v107
	v_cvt_pk_bf16_f32 v98, v100, v101
	v_cvt_pk_bf16_f32 v99, v102, v103
	global_store_dwordx4 v[108:109], v[96:99], off nt
	v_pk_mul_f32 v[94:95], v[94:95], v[90:91]
	v_pk_mul_f32 v[90:91], v[90:91], s[24:25] op_sel_hi:[1,0]
	v_pk_mul_f32 v[98:99], v[88:89], s[24:25] op_sel_hi:[1,0]
	v_pk_mul_f32 v[88:89], v[92:93], v[88:89]
	v_pk_mul_f32 v[92:93], v[80:81], s[24:25] op_sel_hi:[1,0]
	v_pk_mul_f32 v[80:81], v[84:85], v[80:81]
	v_exp_f32_e32 v92, v92
	v_exp_f32_e32 v93, v93
	v_exp_f32_e32 v98, v98
	v_exp_f32_e32 v99, v99
	v_exp_f32_e32 v90, v90
	v_pk_add_f32 v[92:93], v[92:93], 1.0 op_sel_hi:[1,0]
	v_exp_f32_e32 v91, v91
	v_rcp_f32_e32 v92, v92
	v_rcp_f32_e32 v93, v93
	v_pk_add_f32 v[98:99], v[98:99], 1.0 op_sel_hi:[1,0]
	v_pk_add_f32 v[90:91], v[90:91], 1.0 op_sel_hi:[1,0]
	v_rcp_f32_e32 v98, v98
	v_pk_mul_f32 v[84:85], v[80:81], v[92:93]
	v_pk_mul_f32 v[80:81], v[82:83], s[24:25] op_sel_hi:[1,0]
	v_rcp_f32_e32 v99, v99
	v_exp_f32_e32 v80, v80
	v_exp_f32_e32 v81, v81
	v_rcp_f32_e32 v90, v90
	v_rcp_f32_e32 v91, v91
	v_or_b32_e32 v96, 32, v160
	v_pk_add_f32 v[80:81], v[80:81], 1.0 op_sel_hi:[1,0]
	v_mad_i64_i32 v[96:97], s[6:7], v96, s87, v[138:139]
	v_rcp_f32_e32 v80, v80
	v_rcp_f32_e32 v81, v81
	v_pk_mul_f32 v[86:87], v[86:87], v[82:83]
	v_pk_mul_f32 v[88:89], v[88:89], v[98:99]
	v_pk_mul_f32 v[90:91], v[94:95], v[90:91]
	v_pk_mul_f32 v[86:87], v[86:87], v[80:81]
	v_lshl_add_u64 v[92:93], v[96:97], 0, v[112:113]
	v_cvt_pk_bf16_f32 v80, v88, v89
	v_cvt_pk_bf16_f32 v81, v90, v91
	v_cvt_pk_bf16_f32 v82, v84, v85
	v_cvt_pk_bf16_f32 v83, v86, v87
	global_store_dwordx4 v[92:93], v[80:83], off nt
	v_pk_mul_f32 v[78:79], v[78:79], v[74:75]
	v_pk_mul_f32 v[74:75], v[74:75], s[24:25] op_sel_hi:[1,0]
	v_pk_mul_f32 v[82:83], v[72:73], s[24:25] op_sel_hi:[1,0]
	v_pk_mul_f32 v[72:73], v[76:77], v[72:73]
	v_pk_mul_f32 v[76:77], v[64:65], s[24:25] op_sel_hi:[1,0]
	v_pk_mul_f32 v[64:65], v[68:69], v[64:65]
	v_exp_f32_e32 v76, v76
	v_exp_f32_e32 v77, v77
	v_exp_f32_e32 v82, v82
	v_exp_f32_e32 v83, v83
	v_exp_f32_e32 v74, v74
	v_pk_add_f32 v[76:77], v[76:77], 1.0 op_sel_hi:[1,0]
	v_exp_f32_e32 v75, v75
	v_rcp_f32_e32 v76, v76
	v_rcp_f32_e32 v77, v77
	v_pk_add_f32 v[82:83], v[82:83], 1.0 op_sel_hi:[1,0]
	v_pk_add_f32 v[74:75], v[74:75], 1.0 op_sel_hi:[1,0]
	v_rcp_f32_e32 v82, v82
	v_pk_mul_f32 v[68:69], v[64:65], v[76:77]
	v_pk_mul_f32 v[64:65], v[66:67], s[24:25] op_sel_hi:[1,0]
	v_rcp_f32_e32 v83, v83
	v_exp_f32_e32 v64, v64
	v_exp_f32_e32 v65, v65
	v_rcp_f32_e32 v74, v74
	v_rcp_f32_e32 v75, v75
	v_or_b32_e32 v80, 48, v160
	v_pk_add_f32 v[64:65], v[64:65], 1.0 op_sel_hi:[1,0]
	v_mad_i64_i32 v[80:81], s[6:7], v80, s87, v[138:139]
	v_rcp_f32_e32 v64, v64
	v_rcp_f32_e32 v65, v65
	v_pk_mul_f32 v[70:71], v[70:71], v[66:67]
	v_pk_mul_f32 v[72:73], v[72:73], v[82:83]
	v_pk_mul_f32 v[74:75], v[78:79], v[74:75]
	v_pk_mul_f32 v[70:71], v[70:71], v[64:65]
	v_lshl_add_u64 v[76:77], v[80:81], 0, v[112:113]
	v_cvt_pk_bf16_f32 v64, v72, v73
	v_cvt_pk_bf16_f32 v65, v74, v75
	v_cvt_pk_bf16_f32 v66, v68, v69
	v_cvt_pk_bf16_f32 v67, v70, v71
	global_store_dwordx4 v[76:77], v[64:67], off nt
	v_pk_mul_f32 v[62:63], v[62:63], v[58:59]
	v_pk_mul_f32 v[58:59], v[58:59], s[24:25] op_sel_hi:[1,0]
	v_pk_mul_f32 v[66:67], v[56:57], s[24:25] op_sel_hi:[1,0]
	v_pk_mul_f32 v[56:57], v[60:61], v[56:57]
	v_pk_mul_f32 v[60:61], v[48:49], s[24:25] op_sel_hi:[1,0]
	v_pk_mul_f32 v[48:49], v[52:53], v[48:49]
	v_exp_f32_e32 v60, v60
	v_exp_f32_e32 v61, v61
	v_exp_f32_e32 v66, v66
	v_exp_f32_e32 v67, v67
	v_exp_f32_e32 v58, v58
	v_pk_add_f32 v[60:61], v[60:61], 1.0 op_sel_hi:[1,0]
	v_exp_f32_e32 v59, v59
	v_rcp_f32_e32 v60, v60
	v_rcp_f32_e32 v61, v61
	v_pk_add_f32 v[66:67], v[66:67], 1.0 op_sel_hi:[1,0]
	v_pk_add_f32 v[58:59], v[58:59], 1.0 op_sel_hi:[1,0]
	v_rcp_f32_e32 v66, v66
	v_pk_mul_f32 v[52:53], v[48:49], v[60:61]
	v_pk_mul_f32 v[48:49], v[50:51], s[24:25] op_sel_hi:[1,0]
	v_rcp_f32_e32 v67, v67
	v_exp_f32_e32 v48, v48
	v_exp_f32_e32 v49, v49
	v_rcp_f32_e32 v58, v58
	v_rcp_f32_e32 v59, v59
	v_add_u32_e32 v64, 0x80, v160
	v_pk_add_f32 v[48:49], v[48:49], 1.0 op_sel_hi:[1,0]
	v_mad_i64_i32 v[64:65], s[6:7], v64, s87, v[138:139]
	v_rcp_f32_e32 v48, v48
	v_rcp_f32_e32 v49, v49
	v_pk_mul_f32 v[54:55], v[54:55], v[50:51]
	v_pk_mul_f32 v[56:57], v[56:57], v[66:67]
	v_pk_mul_f32 v[58:59], v[62:63], v[58:59]
	v_pk_mul_f32 v[54:55], v[54:55], v[48:49]
	v_lshl_add_u64 v[60:61], v[64:65], 0, v[112:113]
	v_cvt_pk_bf16_f32 v48, v56, v57
	v_cvt_pk_bf16_f32 v49, v58, v59
	v_cvt_pk_bf16_f32 v50, v52, v53
	v_cvt_pk_bf16_f32 v51, v54, v55
	global_store_dwordx4 v[60:61], v[48:51], off nt
	v_pk_mul_f32 v[46:47], v[46:47], v[42:43]
	v_pk_mul_f32 v[42:43], v[42:43], s[24:25] op_sel_hi:[1,0]
	v_pk_mul_f32 v[50:51], v[40:41], s[24:25] op_sel_hi:[1,0]
	v_pk_mul_f32 v[40:41], v[44:45], v[40:41]
	v_pk_mul_f32 v[44:45], v[32:33], s[24:25] op_sel_hi:[1,0]
	v_pk_mul_f32 v[32:33], v[36:37], v[32:33]
	v_exp_f32_e32 v44, v44
	v_exp_f32_e32 v45, v45
	v_exp_f32_e32 v50, v50
	v_exp_f32_e32 v51, v51
	v_exp_f32_e32 v42, v42
	v_pk_add_f32 v[44:45], v[44:45], 1.0 op_sel_hi:[1,0]
	v_exp_f32_e32 v43, v43
	v_rcp_f32_e32 v44, v44
	v_rcp_f32_e32 v45, v45
	v_pk_add_f32 v[50:51], v[50:51], 1.0 op_sel_hi:[1,0]
	v_pk_add_f32 v[42:43], v[42:43], 1.0 op_sel_hi:[1,0]
	v_rcp_f32_e32 v50, v50
	v_pk_mul_f32 v[36:37], v[32:33], v[44:45]
	v_pk_mul_f32 v[32:33], v[34:35], s[24:25] op_sel_hi:[1,0]
	v_rcp_f32_e32 v51, v51
	v_exp_f32_e32 v32, v32
	v_exp_f32_e32 v33, v33
	v_rcp_f32_e32 v42, v42
	v_rcp_f32_e32 v43, v43
	v_add_u32_e32 v48, 0x90, v160
	v_pk_add_f32 v[32:33], v[32:33], 1.0 op_sel_hi:[1,0]
	v_mad_i64_i32 v[48:49], s[6:7], v48, s87, v[138:139]
	v_rcp_f32_e32 v32, v32
	v_rcp_f32_e32 v33, v33
	v_pk_mul_f32 v[38:39], v[38:39], v[34:35]
	v_pk_mul_f32 v[40:41], v[40:41], v[50:51]
	v_pk_mul_f32 v[42:43], v[46:47], v[42:43]
	v_pk_mul_f32 v[38:39], v[38:39], v[32:33]
	v_lshl_add_u64 v[44:45], v[48:49], 0, v[112:113]
	v_cvt_pk_bf16_f32 v32, v40, v41
	v_cvt_pk_bf16_f32 v33, v42, v43
	v_cvt_pk_bf16_f32 v34, v36, v37
	v_cvt_pk_bf16_f32 v35, v38, v39
	global_store_dwordx4 v[44:45], v[32:35], off nt
	v_pk_mul_f32 v[30:31], v[30:31], v[26:27]
	v_pk_mul_f32 v[26:27], v[26:27], s[24:25] op_sel_hi:[1,0]
	v_pk_mul_f32 v[34:35], v[24:25], s[24:25] op_sel_hi:[1,0]
	v_pk_mul_f32 v[24:25], v[28:29], v[24:25]
	v_pk_mul_f32 v[28:29], v[16:17], s[24:25] op_sel_hi:[1,0]
	v_pk_mul_f32 v[16:17], v[20:21], v[16:17]
	v_exp_f32_e32 v28, v28
	v_exp_f32_e32 v29, v29
	v_exp_f32_e32 v34, v34
	v_exp_f32_e32 v35, v35
	v_exp_f32_e32 v26, v26
	v_pk_add_f32 v[28:29], v[28:29], 1.0 op_sel_hi:[1,0]
	v_exp_f32_e32 v27, v27
	v_rcp_f32_e32 v28, v28
	v_rcp_f32_e32 v29, v29
	v_pk_add_f32 v[34:35], v[34:35], 1.0 op_sel_hi:[1,0]
	v_pk_add_f32 v[26:27], v[26:27], 1.0 op_sel_hi:[1,0]
	v_rcp_f32_e32 v34, v34
	v_pk_mul_f32 v[20:21], v[16:17], v[28:29]
	v_pk_mul_f32 v[16:17], v[18:19], s[24:25] op_sel_hi:[1,0]
	v_rcp_f32_e32 v35, v35
	v_exp_f32_e32 v16, v16
	v_exp_f32_e32 v17, v17
	v_rcp_f32_e32 v26, v26
	v_rcp_f32_e32 v27, v27
	v_add_u32_e32 v32, 0xa0, v160
	v_pk_add_f32 v[16:17], v[16:17], 1.0 op_sel_hi:[1,0]
	v_mad_i64_i32 v[32:33], s[6:7], v32, s87, v[138:139]
	v_rcp_f32_e32 v16, v16
	v_rcp_f32_e32 v17, v17
	v_pk_mul_f32 v[22:23], v[22:23], v[18:19]
	v_pk_mul_f32 v[24:25], v[24:25], v[34:35]
	v_pk_mul_f32 v[26:27], v[30:31], v[26:27]
	v_pk_mul_f32 v[22:23], v[22:23], v[16:17]
	v_lshl_add_u64 v[28:29], v[32:33], 0, v[112:113]
	v_cvt_pk_bf16_f32 v16, v24, v25
	v_cvt_pk_bf16_f32 v17, v26, v27
	v_cvt_pk_bf16_f32 v18, v20, v21
	v_cvt_pk_bf16_f32 v19, v22, v23
	global_store_dwordx4 v[28:29], v[16:19], off nt
	v_pk_mul_f32 v[14:15], v[14:15], v[10:11]
	v_pk_mul_f32 v[10:11], v[10:11], s[24:25] op_sel_hi:[1,0]
	v_pk_mul_f32 v[18:19], v[8:9], s[24:25] op_sel_hi:[1,0]
	v_pk_mul_f32 v[8:9], v[12:13], v[8:9]
	v_pk_mul_f32 v[12:13], v[0:1], s[24:25] op_sel_hi:[1,0]
	v_pk_mul_f32 v[0:1], v[4:5], v[0:1]
	v_exp_f32_e32 v12, v12
	v_exp_f32_e32 v13, v13
	v_exp_f32_e32 v18, v18
	v_exp_f32_e32 v19, v19
	v_exp_f32_e32 v10, v10
	v_pk_add_f32 v[12:13], v[12:13], 1.0 op_sel_hi:[1,0]
	v_exp_f32_e32 v11, v11
	v_rcp_f32_e32 v12, v12
	v_rcp_f32_e32 v13, v13
	v_pk_add_f32 v[18:19], v[18:19], 1.0 op_sel_hi:[1,0]
	v_pk_add_f32 v[10:11], v[10:11], 1.0 op_sel_hi:[1,0]
	v_rcp_f32_e32 v18, v18
	v_pk_mul_f32 v[4:5], v[0:1], v[12:13]
	v_pk_mul_f32 v[0:1], v[2:3], s[24:25] op_sel_hi:[1,0]
	v_rcp_f32_e32 v19, v19
	v_exp_f32_e32 v0, v0
	v_exp_f32_e32 v1, v1
	v_rcp_f32_e32 v10, v10
	v_rcp_f32_e32 v11, v11
	v_add_u32_e32 v16, 0xb0, v160
	v_pk_add_f32 v[0:1], v[0:1], 1.0 op_sel_hi:[1,0]
	v_mad_i64_i32 v[16:17], s[6:7], v16, s87, v[138:139]
	v_rcp_f32_e32 v0, v0
	v_rcp_f32_e32 v1, v1
	v_pk_mul_f32 v[6:7], v[6:7], v[2:3]
	v_lshl_add_u64 v[12:13], v[16:17], 0, v[112:113]
	s_and_b64 vcc, exec, s[38:39]
	s_mov_b32 s69, s61
	s_mov_b32 s70, s68
	s_mov_b64 s[6:7], s[44:45]
	s_mov_b64 s[8:9], s[42:43]
	v_pk_mul_f32 v[8:9], v[8:9], v[18:19]
	v_pk_mul_f32 v[10:11], v[14:15], v[10:11]
	v_pk_mul_f32 v[6:7], v[6:7], v[0:1]
	v_cvt_pk_bf16_f32 v0, v8, v9
	v_cvt_pk_bf16_f32 v1, v10, v11
	v_cvt_pk_bf16_f32 v2, v4, v5
	s_nop 0
	v_cvt_pk_bf16_f32 v3, v6, v7
	global_store_dwordx4 v[12:13], v[0:3], off nt
	s_cbranch_vccnz .LBB0_1060
